# GEMM0: blocks 256..511 (the second block of each CU) start the phase 1280 cycles later so CU partners sit half a K iteration apart
# speedup vs baseline: 1.0013x; 1.0013x over previous
.LBB0_368:
	s_cmpk_gt_i32 s42, 0xbf
	s_cbranch_scc1 .LBB0_521
	s_mov_b32 s43, s42
	v_readlane_b32 s0, v209, 0
	s_nop 3
	s_cmpk_lt_u32 s0, 0x100
	s_cbranch_scc1 .Lstg_skip
	s_sleep 20
.Lstg_skip:
	s_mov_b32 s0, s42
	s_mul_hi_i32 s1, s0, 0x55555556
	s_lshr_b32 s4, s1, 31
	s_add_i32 s1, s1, s4
	s_mul_i32 s4, s1, 3
	s_sub_i32 s4, s0, s4
	s_lshl_b32 s4, s4, 3
	s_add_i32 s4, s4, s41
	s_lshl_b32 s4, s4, 7
	s_lshl_b32 s1, s1, 7
	v_lshrrev_b32_e32 v200, 3, v0
	v_and_b32_e32 v201, 7, v0
	v_lshlrev_b32_e32 v201, 4, v201
	v_add_u32_e32 v202, s1, v200
	v_add_u32_e32 v203, s4, v200
	s_movk_i32 s0, 0x880
	v_mul_lo_u32 v202, v202, s0
	v_mul_lo_u32 v203, v203, s0
	v_add_u32_e32 v202, v202, v201
	v_add_u32_e32 v203, v203, v201
	v_add_u32_e32 v210, 0x11000, v202
	v_add_u32_e32 v211, 0x22000, v202
	v_add_u32_e32 v212, 0x33000, v202
	v_add_u32_e32 v213, 0x11000, v203
	v_add_u32_e32 v214, 0x22000, v203
	v_add_u32_e32 v215, 0x33000, v203
	global_load_dwordx4 v[164:167], v202, s[66:67]
	global_load_dwordx4 v[168:171], v210, s[66:67]
	global_load_dwordx4 v[172:175], v211, s[66:67]
	global_load_dwordx4 v[176:179], v212, s[66:67]
	global_load_dwordx4 v[180:183], v203, s[2:3]
	global_load_dwordx4 v[184:187], v213, s[2:3]
	global_load_dwordx4 v[192:195], v214, s[2:3]
	global_load_dwordx4 v[196:199], v215, s[2:3]
	s_branch .LBB0_372
